# prep: non-temporal hint on the one-shot adaLN-matrix and f32-weight reads
# speedup vs baseline: 1.0052x; 1.0052x over previous
.LBB0_1135:
	s_or_b64 exec, exec, s[18:19]
	v_mul_lo_u16_e32 v5, v7, v6
	v_sub_u16_e32 v4, v4, v5
	v_lshlrev_b32_sdwa v50, v223, sext(v4) dst_sel:DWORD dst_unused:UNUSED_PAD src0_sel:DWORD src1_sel:WORD_0
	v_mov_b32_e32 v68, v202
	v_cmp_lt_i32_e32 vcc, -1, v0
	s_and_saveexec_b64 s[18:19], vcc
	s_cbranch_execz .LBB0_1153
	v_lshlrev_b32_e32 v4, 2, v68
	v_and_b32_e32 v69, 60, v4
	v_lshl_add_u64 v[2:3], v[0:1], 2, v[2:3]
	v_lshlrev_b32_e32 v4, 2, v69
	v_mov_b32_e32 v5, v1
	v_ashrrev_i32_e32 v70, 4, v68
	v_lshl_add_u64 v[52:53], v[2:3], 0, v[4:5]
	v_add_u32_e32 v3, v70, v50
	v_cmp_lt_i32_e32 vcc, v3, v66
	v_mov_b32_e32 v2, 0
	v_mov_b32_e32 v6, 0
	v_mov_b32_e32 v7, 0
	v_mov_b32_e32 v8, 0
	v_mov_b32_e32 v9, 0
	s_and_saveexec_b64 s[20:21], vcc
	s_cbranch_execz .LBB0_1138
	v_ashrrev_i32_e32 v4, 31, v3
	v_mul_lo_u32 v6, v49, v3
	v_mul_lo_u32 v7, v48, v4
	v_mad_u64_u32 v[4:5], s[12:13], v48, v3, 0
	v_add3_u32 v5, v5, v7, v6
	v_lshl_add_u64 v[4:5], v[4:5], 2, v[52:53]
	global_load_dwordx4 v[6:9], v[4:5], off nt
.LBB0_1138:
	s_or_b64 exec, exec, s[20:21]
	v_add_u32_e32 v3, 0x200, v68
	v_ashrrev_i32_e32 v71, 4, v3
	v_add_u32_e32 v10, v71, v50
	v_cmp_lt_i32_e32 vcc, v10, v66
	v_mov_b32_e32 v3, 0
	v_mov_b32_e32 v4, 0
	v_mov_b32_e32 v5, 0
	s_and_saveexec_b64 s[20:21], vcc
	s_cbranch_execz .LBB0_1140
	v_ashrrev_i32_e32 v2, 31, v10
	v_mul_lo_u32 v4, v49, v10
	v_mul_lo_u32 v5, v48, v2
	v_mad_u64_u32 v[2:3], s[12:13], v48, v10, 0
	v_add3_u32 v3, v3, v5, v4
	v_lshl_add_u64 v[2:3], v[2:3], 2, v[52:53]
	global_load_dwordx4 v[2:5], v[2:3], off nt
.LBB0_1140:
	s_or_b64 exec, exec, s[20:21]
	v_add_u32_e32 v10, 0x400, v68
	v_ashrrev_i32_e32 v72, 4, v10
	v_add_u32_e32 v11, v72, v50
	v_cmp_lt_i32_e32 vcc, v11, v66
	v_mov_b32_e32 v10, 0
	v_mov_b32_e32 v14, 0
	v_mov_b32_e32 v15, 0
	v_mov_b32_e32 v16, 0
	v_mov_b32_e32 v17, 0
	s_and_saveexec_b64 s[20:21], vcc
	s_cbranch_execz .LBB0_1142
	v_ashrrev_i32_e32 v12, 31, v11
	v_mul_lo_u32 v14, v49, v11
	v_mul_lo_u32 v15, v48, v12
	v_mad_u64_u32 v[12:13], s[12:13], v48, v11, 0
	v_add3_u32 v13, v13, v15, v14
	v_lshl_add_u64 v[12:13], v[12:13], 2, v[52:53]
	global_load_dwordx4 v[14:17], v[12:13], off nt
.LBB0_1142:
	s_or_b64 exec, exec, s[20:21]
	v_add_u32_e32 v11, 0x600, v68
	v_ashrrev_i32_e32 v73, 4, v11
	v_add_u32_e32 v18, v73, v50
	v_cmp_lt_i32_e32 vcc, v18, v66
	v_mov_b32_e32 v11, 0
	v_mov_b32_e32 v12, 0
	v_mov_b32_e32 v13, 0
	s_and_saveexec_b64 s[20:21], vcc
	s_cbranch_execz .LBB0_1144
	v_ashrrev_i32_e32 v10, 31, v18
	v_mul_lo_u32 v12, v49, v18
	v_mul_lo_u32 v13, v48, v10
	v_mad_u64_u32 v[10:11], s[12:13], v48, v18, 0
	v_add3_u32 v11, v11, v13, v12
	v_lshl_add_u64 v[10:11], v[10:11], 2, v[52:53]
	global_load_dwordx4 v[10:13], v[10:11], off nt
.LBB0_1144:
	s_or_b64 exec, exec, s[20:21]
	v_add_u32_e32 v18, 0x800, v68
	v_ashrrev_i32_e32 v74, 4, v18
	v_add_u32_e32 v19, v74, v50
	v_cmp_lt_i32_e32 vcc, v19, v66
	v_mov_b32_e32 v18, 0
	v_mov_b32_e32 v22, 0
	v_mov_b32_e32 v23, 0
	v_mov_b32_e32 v24, 0
	v_mov_b32_e32 v25, 0
	s_and_saveexec_b64 s[20:21], vcc
	s_cbranch_execz .LBB0_1146
	v_ashrrev_i32_e32 v20, 31, v19
	v_mul_lo_u32 v22, v49, v19
	v_mul_lo_u32 v23, v48, v20
	v_mad_u64_u32 v[20:21], s[12:13], v48, v19, 0
	v_add3_u32 v21, v21, v23, v22
	v_lshl_add_u64 v[20:21], v[20:21], 2, v[52:53]
	global_load_dwordx4 v[22:25], v[20:21], off nt
.LBB0_1146:
	s_or_b64 exec, exec, s[20:21]
	v_add_u32_e32 v19, 0xa00, v68
	v_ashrrev_i32_e32 v75, 4, v19
	v_add_u32_e32 v26, v75, v50
	v_cmp_lt_i32_e32 vcc, v26, v66
	v_mov_b32_e32 v19, 0
	v_mov_b32_e32 v20, 0
	v_mov_b32_e32 v21, 0
	s_and_saveexec_b64 s[20:21], vcc
	s_cbranch_execz .LBB0_1148
	v_ashrrev_i32_e32 v18, 31, v26
	v_mul_lo_u32 v20, v49, v26
	v_mul_lo_u32 v21, v48, v18
	v_mad_u64_u32 v[18:19], s[12:13], v48, v26, 0
	v_add3_u32 v19, v19, v21, v20
	v_lshl_add_u64 v[18:19], v[18:19], 2, v[52:53]
	global_load_dwordx4 v[18:21], v[18:19], off nt
.LBB0_1148:
	s_or_b64 exec, exec, s[20:21]
	v_add_u32_e32 v26, 0xc00, v68
	v_ashrrev_i32_e32 v76, 4, v26
	v_add_u32_e32 v27, v76, v50
	v_cmp_lt_i32_e32 vcc, v27, v66
	v_mov_b32_e32 v26, 0
	v_mov_b32_e32 v30, 0
	v_mov_b32_e32 v31, 0
	v_mov_b32_e32 v32, 0
	v_mov_b32_e32 v33, 0
	s_and_saveexec_b64 s[20:21], vcc
	s_cbranch_execz .LBB0_1150
	v_ashrrev_i32_e32 v28, 31, v27
	v_mul_lo_u32 v30, v49, v27
	v_mul_lo_u32 v31, v48, v28
	v_mad_u64_u32 v[28:29], s[12:13], v48, v27, 0
	v_add3_u32 v29, v29, v31, v30
	v_lshl_add_u64 v[28:29], v[28:29], 2, v[52:53]
	global_load_dwordx4 v[30:33], v[28:29], off nt
.LBB0_1150:
	s_or_b64 exec, exec, s[20:21]
	v_add_u32_e32 v27, 0xe00, v68
	v_ashrrev_i32_e32 v77, 4, v27
	v_add_u32_e32 v78, v77, v50
	v_cmp_lt_i32_e32 vcc, v78, v66
	v_mov_b32_e32 v27, 0
	v_mov_b32_e32 v28, 0
	v_mov_b32_e32 v29, 0
	s_and_saveexec_b64 s[20:21], vcc
	s_cbranch_execz .LBB0_1152
	v_ashrrev_i32_e32 v26, 31, v78
	v_mul_lo_u32 v28, v49, v78
	v_mul_lo_u32 v29, v48, v26
	v_mad_u64_u32 v[26:27], s[12:13], v48, v78, 0
	v_add3_u32 v27, v27, v29, v28
	v_lshl_add_u64 v[26:27], v[26:27], 2, v[52:53]
	global_load_dwordx4 v[26:29], v[26:27], off nt

.LBB0_1222:
	v_add_co_u32_e32 v184, vcc, 0xfffd6000, v4
	s_nop 1
	v_addc_co_u32_e32 v185, vcc, -1, v5, vcc
	v_add_u32_e32 v186, 0x14000, v62
	global_load_dword v112, v[184:185], off nt
	v_add_co_u32_e32 v184, vcc, 0x6000, v184
	s_nop 1
	v_addc_co_u32_e32 v185, vcc, 0, v185, vcc
	global_load_dword v113, v[184:185], off nt
	v_add_co_u32_e32 v184, vcc, 0x6000, v184
	s_nop 1
	v_addc_co_u32_e32 v185, vcc, 0, v185, vcc
	global_load_dword v114, v[184:185], off nt
	v_add_co_u32_e32 v184, vcc, 0x6000, v184
	s_nop 1
	v_addc_co_u32_e32 v185, vcc, 0, v185, vcc
	global_load_dword v115, v[184:185], off nt
	v_add_co_u32_e32 v184, vcc, 0x6000, v184
	s_nop 1
	v_addc_co_u32_e32 v185, vcc, 0, v185, vcc
	global_load_dword v116, v[184:185], off nt
	v_add_co_u32_e32 v184, vcc, 0x6000, v184
	s_nop 1
	v_addc_co_u32_e32 v185, vcc, 0, v185, vcc
	global_load_dword v117, v[184:185], off nt
	v_add_co_u32_e32 v184, vcc, 0x6000, v184
	s_nop 1
	v_addc_co_u32_e32 v185, vcc, 0, v185, vcc
	global_load_dword v118, v[184:185], off nt
	v_add_co_u32_e32 v184, vcc, 0x6000, v184
	s_nop 1
	v_addc_co_u32_e32 v185, vcc, 0, v185, vcc
	global_load_dword v119, v[184:185], off nt
	v_add_co_u32_e32 v184, vcc, 0x6000, v184
	s_nop 1
	v_addc_co_u32_e32 v185, vcc, 0, v185, vcc
	global_load_dword v120, v[184:185], off nt
	v_add_co_u32_e32 v184, vcc, 0x6000, v184
	s_nop 1
	v_addc_co_u32_e32 v185, vcc, 0, v185, vcc
	global_load_dword v121, v[184:185], off nt
	v_add_co_u32_e32 v184, vcc, 0x6000, v184
	s_nop 1
	v_addc_co_u32_e32 v185, vcc, 0, v185, vcc
	global_load_dword v122, v[184:185], off nt
	v_add_co_u32_e32 v184, vcc, 0x6000, v184
	s_nop 1
	v_addc_co_u32_e32 v185, vcc, 0, v185, vcc
	global_load_dword v123, v[184:185], off nt
	v_add_co_u32_e32 v184, vcc, 0x6000, v184
	s_nop 1
	v_addc_co_u32_e32 v185, vcc, 0, v185, vcc
	global_load_dword v124, v[184:185], off nt
	v_add_co_u32_e32 v184, vcc, 0x6000, v184
	s_nop 1
	v_addc_co_u32_e32 v185, vcc, 0, v185, vcc
	global_load_dword v125, v[184:185], off nt
	v_add_co_u32_e32 v184, vcc, 0x6000, v184
	s_nop 1
	v_addc_co_u32_e32 v185, vcc, 0, v185, vcc
	global_load_dword v126, v[184:185], off nt
	v_add_co_u32_e32 v184, vcc, 0x6000, v184
	s_nop 1
	v_addc_co_u32_e32 v185, vcc, 0, v185, vcc
	global_load_dword v127, v[184:185], off nt
	v_add_co_u32_e32 v184, vcc, 0x6000, v184
	s_nop 1
	v_addc_co_u32_e32 v185, vcc, 0, v185, vcc
	global_load_dword v128, v[184:185], off nt
	v_add_co_u32_e32 v184, vcc, 0x6000, v184
	s_nop 1
	v_addc_co_u32_e32 v185, vcc, 0, v185, vcc
	global_load_dword v129, v[184:185], off nt
	v_add_co_u32_e32 v184, vcc, 0x6000, v184
	s_nop 1
	v_addc_co_u32_e32 v185, vcc, 0, v185, vcc
	global_load_dword v130, v[184:185], off nt
	v_add_co_u32_e32 v184, vcc, 0x6000, v184
	s_nop 1
	v_addc_co_u32_e32 v185, vcc, 0, v185, vcc
	global_load_dword v131, v[184:185], off nt
	v_add_co_u32_e32 v184, vcc, 0x6000, v184
	s_nop 1
	v_addc_co_u32_e32 v185, vcc, 0, v185, vcc
	global_load_dword v132, v[184:185], off nt
	v_add_co_u32_e32 v184, vcc, 0x6000, v184
	s_nop 1
	v_addc_co_u32_e32 v185, vcc, 0, v185, vcc
	global_load_dword v133, v[184:185], off nt
	v_add_co_u32_e32 v184, vcc, 0x6000, v184
	s_nop 1
	v_addc_co_u32_e32 v185, vcc, 0, v185, vcc
	global_load_dword v134, v[184:185], off nt
	v_add_co_u32_e32 v184, vcc, 0x6000, v184
	s_nop 1
	v_addc_co_u32_e32 v185, vcc, 0, v185, vcc
	global_load_dword v135, v[184:185], off nt
	v_add_co_u32_e32 v184, vcc, 0x6000, v184
	s_nop 1
	v_addc_co_u32_e32 v185, vcc, 0, v185, vcc
	global_load_dword v136, v[184:185], off nt
	v_add_co_u32_e32 v184, vcc, 0x6000, v184
	s_nop 1
	v_addc_co_u32_e32 v185, vcc, 0, v185, vcc
	global_load_dword v137, v[184:185], off nt
	v_add_co_u32_e32 v184, vcc, 0x6000, v184
	s_nop 1
	v_addc_co_u32_e32 v185, vcc, 0, v185, vcc
	global_load_dword v138, v[184:185], off nt
	v_add_co_u32_e32 v184, vcc, 0x6000, v184
	s_nop 1
	v_addc_co_u32_e32 v185, vcc, 0, v185, vcc
	global_load_dword v139, v[184:185], off nt
	v_add_co_u32_e32 v184, vcc, 0x6000, v184
	s_nop 1
	v_addc_co_u32_e32 v185, vcc, 0, v185, vcc
	global_load_dword v140, v[184:185], off nt
	v_add_co_u32_e32 v184, vcc, 0x6000, v184
	s_nop 1
	v_addc_co_u32_e32 v185, vcc, 0, v185, vcc
	global_load_dword v141, v[184:185], off nt
	v_add_co_u32_e32 v184, vcc, 0x6000, v184
	s_nop 1
	v_addc_co_u32_e32 v185, vcc, 0, v185, vcc
	global_load_dword v142, v[184:185], off nt
	v_add_co_u32_e32 v184, vcc, 0x6000, v184
	s_nop 1
	v_addc_co_u32_e32 v185, vcc, 0, v185, vcc
	global_load_dword v143, v[184:185], off nt
	v_add_co_u32_e32 v184, vcc, 0x6000, v184
	s_nop 1
	v_addc_co_u32_e32 v185, vcc, 0, v185, vcc
	global_load_dword v144, v[184:185], off nt
	v_add_co_u32_e32 v184, vcc, 0x6000, v184
	s_nop 1
	v_addc_co_u32_e32 v185, vcc, 0, v185, vcc
	global_load_dword v145, v[184:185], off nt
	v_add_co_u32_e32 v184, vcc, 0x6000, v184
	s_nop 1
	v_addc_co_u32_e32 v185, vcc, 0, v185, vcc
	global_load_dword v146, v[184:185], off nt
	v_add_co_u32_e32 v184, vcc, 0x6000, v184
	s_nop 1
	v_addc_co_u32_e32 v185, vcc, 0, v185, vcc
	global_load_dword v147, v[184:185], off nt
	v_add_co_u32_e32 v184, vcc, 0x6000, v184
	s_nop 1
	v_addc_co_u32_e32 v185, vcc, 0, v185, vcc
	global_load_dword v148, v[184:185], off nt
	v_add_co_u32_e32 v184, vcc, 0x6000, v184
	s_nop 1
	v_addc_co_u32_e32 v185, vcc, 0, v185, vcc
	global_load_dword v149, v[184:185], off nt
	v_add_co_u32_e32 v184, vcc, 0x6000, v184
	s_nop 1
	v_addc_co_u32_e32 v185, vcc, 0, v185, vcc
	global_load_dword v150, v[184:185], off nt
	v_add_co_u32_e32 v184, vcc, 0x6000, v184
	s_nop 1
	v_addc_co_u32_e32 v185, vcc, 0, v185, vcc
	global_load_dword v151, v[184:185], off nt
	v_add_co_u32_e32 v184, vcc, 0x6000, v184
	s_nop 1
	v_addc_co_u32_e32 v185, vcc, 0, v185, vcc
	global_load_dword v152, v[184:185], off nt
	v_add_co_u32_e32 v184, vcc, 0x6000, v184
	s_nop 1
	v_addc_co_u32_e32 v185, vcc, 0, v185, vcc
	global_load_dword v153, v[184:185], off nt
	v_add_co_u32_e32 v184, vcc, 0x6000, v184
	s_nop 1
	v_addc_co_u32_e32 v185, vcc, 0, v185, vcc
	global_load_dword v154, v[184:185], off nt
	v_add_co_u32_e32 v184, vcc, 0x6000, v184
	s_nop 1
	v_addc_co_u32_e32 v185, vcc, 0, v185, vcc
	global_load_dword v155, v[184:185], off nt
	v_add_co_u32_e32 v184, vcc, 0x6000, v184
	s_nop 1
	v_addc_co_u32_e32 v185, vcc, 0, v185, vcc
	global_load_dword v156, v[184:185], off nt
	v_add_co_u32_e32 v184, vcc, 0x6000, v184
	s_nop 1
	v_addc_co_u32_e32 v185, vcc, 0, v185, vcc
	global_load_dword v157, v[184:185], off nt
	v_add_co_u32_e32 v184, vcc, 0x6000, v184
	s_nop 1
	v_addc_co_u32_e32 v185, vcc, 0, v185, vcc
	global_load_dword v158, v[184:185], off nt
	v_add_co_u32_e32 v184, vcc, 0x6000, v184
	s_nop 1
	v_addc_co_u32_e32 v185, vcc, 0, v185, vcc
	global_load_dword v159, v[184:185], off nt
	v_add_co_u32_e32 v184, vcc, 0x6000, v184
	s_nop 1
	v_addc_co_u32_e32 v185, vcc, 0, v185, vcc
	ds_read_b128 v[8:11], v186 offset:0
	ds_read_b128 v[12:15], v186 offset:4096
	ds_read_b128 v[16:19], v186 offset:8192
	ds_read_b128 v[20:23], v186 offset:16
	ds_read_b128 v[24:27], v186 offset:4112
	ds_read_b128 v[28:31], v186 offset:8208
	ds_read_b128 v[188:191], v186 offset:32
	ds_read_b128 v[192:195], v186 offset:4128
	ds_read_b128 v[196:199], v186 offset:8224
	ds_read_b128 v[228:231], v186 offset:48
	ds_read_b128 v[232:235], v186 offset:4144
	ds_read_b128 v[236:239], v186 offset:8240
	s_waitcnt vmcnt(32)
	s_waitcnt lgkmcnt(0)
	v_fmac_f32_e32 v6, v112, v8
	v_fmac_f32_e32 v7, v112, v12
	v_fmac_f32_e32 v3, v112, v16
	v_fmac_f32_e32 v6, v113, v9
	v_fmac_f32_e32 v7, v113, v13
	v_fmac_f32_e32 v3, v113, v17
	v_fmac_f32_e32 v6, v114, v10
	v_fmac_f32_e32 v7, v114, v14
	v_fmac_f32_e32 v3, v114, v18
	v_fmac_f32_e32 v6, v115, v11
	v_fmac_f32_e32 v7, v115, v15
	v_fmac_f32_e32 v3, v115, v19
	v_fmac_f32_e32 v6, v116, v20
	v_fmac_f32_e32 v7, v116, v24
	v_fmac_f32_e32 v3, v116, v28
	v_fmac_f32_e32 v6, v117, v21
	v_fmac_f32_e32 v7, v117, v25
	v_fmac_f32_e32 v3, v117, v29
	v_fmac_f32_e32 v6, v118, v22
	v_fmac_f32_e32 v7, v118, v26
	v_fmac_f32_e32 v3, v118, v30
	v_fmac_f32_e32 v6, v119, v23
	v_fmac_f32_e32 v7, v119, v27
	v_fmac_f32_e32 v3, v119, v31
	v_fmac_f32_e32 v6, v120, v188
	v_fmac_f32_e32 v7, v120, v192
	v_fmac_f32_e32 v3, v120, v196
	v_fmac_f32_e32 v6, v121, v189
	v_fmac_f32_e32 v7, v121, v193
	v_fmac_f32_e32 v3, v121, v197
	v_fmac_f32_e32 v6, v122, v190
	v_fmac_f32_e32 v7, v122, v194
	v_fmac_f32_e32 v3, v122, v198
	v_fmac_f32_e32 v6, v123, v191
	v_fmac_f32_e32 v7, v123, v195
	v_fmac_f32_e32 v3, v123, v199
	v_fmac_f32_e32 v6, v124, v228
	v_fmac_f32_e32 v7, v124, v232
	v_fmac_f32_e32 v3, v124, v236
	v_fmac_f32_e32 v6, v125, v229
	v_fmac_f32_e32 v7, v125, v233
	v_fmac_f32_e32 v3, v125, v237
	v_fmac_f32_e32 v6, v126, v230
	v_fmac_f32_e32 v7, v126, v234
	v_fmac_f32_e32 v3, v126, v238
	v_fmac_f32_e32 v6, v127, v231
	v_fmac_f32_e32 v7, v127, v235
	v_fmac_f32_e32 v3, v127, v239
	global_load_dword v112, v[184:185], off nt
	v_add_co_u32_e32 v184, vcc, 0x6000, v184
	s_nop 1
	v_addc_co_u32_e32 v185, vcc, 0, v185, vcc
	global_load_dword v113, v[184:185], off nt
	v_add_co_u32_e32 v184, vcc, 0x6000, v184
	s_nop 1
	v_addc_co_u32_e32 v185, vcc, 0, v185, vcc
	global_load_dword v114, v[184:185], off nt
	v_add_co_u32_e32 v184, vcc, 0x6000, v184
	s_nop 1
	v_addc_co_u32_e32 v185, vcc, 0, v185, vcc
	global_load_dword v115, v[184:185], off nt
	v_add_co_u32_e32 v184, vcc, 0x6000, v184
	s_nop 1
	v_addc_co_u32_e32 v185, vcc, 0, v185, vcc
	global_load_dword v116, v[184:185], off nt
	v_add_co_u32_e32 v184, vcc, 0x6000, v184
	s_nop 1
	v_addc_co_u32_e32 v185, vcc, 0, v185, vcc
	global_load_dword v117, v[184:185], off nt
	v_add_co_u32_e32 v184, vcc, 0x6000, v184
	s_nop 1
	v_addc_co_u32_e32 v185, vcc, 0, v185, vcc
	global_load_dword v118, v[184:185], off nt
	v_add_co_u32_e32 v184, vcc, 0x6000, v184
	s_nop 1
	v_addc_co_u32_e32 v185, vcc, 0, v185, vcc
	global_load_dword v119, v[184:185], off nt
	v_add_co_u32_e32 v184, vcc, 0x6000, v184
	s_nop 1
	v_addc_co_u32_e32 v185, vcc, 0, v185, vcc
	global_load_dword v120, v[184:185], off nt
	v_add_co_u32_e32 v184, vcc, 0x6000, v184
	s_nop 1
	v_addc_co_u32_e32 v185, vcc, 0, v185, vcc
	global_load_dword v121, v[184:185], off nt
	v_add_co_u32_e32 v184, vcc, 0x6000, v184
	s_nop 1
	v_addc_co_u32_e32 v185, vcc, 0, v185, vcc
	global_load_dword v122, v[184:185], off nt
	v_add_co_u32_e32 v184, vcc, 0x6000, v184
	s_nop 1
	v_addc_co_u32_e32 v185, vcc, 0, v185, vcc
	global_load_dword v123, v[184:185], off nt
	v_add_co_u32_e32 v184, vcc, 0x6000, v184
	s_nop 1
	v_addc_co_u32_e32 v185, vcc, 0, v185, vcc
	global_load_dword v124, v[184:185], off nt
	v_add_co_u32_e32 v184, vcc, 0x6000, v184
	s_nop 1
	v_addc_co_u32_e32 v185, vcc, 0, v185, vcc
	global_load_dword v125, v[184:185], off nt
	v_add_co_u32_e32 v184, vcc, 0x6000, v184
	s_nop 1
	v_addc_co_u32_e32 v185, vcc, 0, v185, vcc
	global_load_dword v126, v[184:185], off nt
	v_add_co_u32_e32 v184, vcc, 0x6000, v184
	s_nop 1
	v_addc_co_u32_e32 v185, vcc, 0, v185, vcc
	global_load_dword v127, v[184:185], off nt
	v_add_co_u32_e32 v184, vcc, 0x6000, v184
	s_nop 1
	v_addc_co_u32_e32 v185, vcc, 0, v185, vcc
	ds_read_b128 v[8:11], v186 offset:64
	ds_read_b128 v[12:15], v186 offset:4160
	ds_read_b128 v[16:19], v186 offset:8256
	ds_read_b128 v[20:23], v186 offset:80
	ds_read_b128 v[24:27], v186 offset:4176
	ds_read_b128 v[28:31], v186 offset:8272
	ds_read_b128 v[188:191], v186 offset:96
	ds_read_b128 v[192:195], v186 offset:4192
	ds_read_b128 v[196:199], v186 offset:8288
	ds_read_b128 v[228:231], v186 offset:112
	ds_read_b128 v[232:235], v186 offset:4208
	ds_read_b128 v[236:239], v186 offset:8304
	s_waitcnt vmcnt(32)
	s_waitcnt lgkmcnt(0)
	v_fmac_f32_e32 v6, v128, v8
	v_fmac_f32_e32 v7, v128, v12
	v_fmac_f32_e32 v3, v128, v16
	v_fmac_f32_e32 v6, v129, v9
	v_fmac_f32_e32 v7, v129, v13
	v_fmac_f32_e32 v3, v129, v17
	v_fmac_f32_e32 v6, v130, v10
	v_fmac_f32_e32 v7, v130, v14
	v_fmac_f32_e32 v3, v130, v18
	v_fmac_f32_e32 v6, v131, v11
	v_fmac_f32_e32 v7, v131, v15
	v_fmac_f32_e32 v3, v131, v19
	v_fmac_f32_e32 v6, v132, v20
	v_fmac_f32_e32 v7, v132, v24
	v_fmac_f32_e32 v3, v132, v28
	v_fmac_f32_e32 v6, v133, v21
	v_fmac_f32_e32 v7, v133, v25
	v_fmac_f32_e32 v3, v133, v29
	v_fmac_f32_e32 v6, v134, v22
	v_fmac_f32_e32 v7, v134, v26
	v_fmac_f32_e32 v3, v134, v30
	v_fmac_f32_e32 v6, v135, v23
	v_fmac_f32_e32 v7, v135, v27
	v_fmac_f32_e32 v3, v135, v31
	v_fmac_f32_e32 v6, v136, v188
	v_fmac_f32_e32 v7, v136, v192
	v_fmac_f32_e32 v3, v136, v196
	v_fmac_f32_e32 v6, v137, v189
	v_fmac_f32_e32 v7, v137, v193
	v_fmac_f32_e32 v3, v137, v197
	v_fmac_f32_e32 v6, v138, v190
	v_fmac_f32_e32 v7, v138, v194
	v_fmac_f32_e32 v3, v138, v198
	v_fmac_f32_e32 v6, v139, v191
	v_fmac_f32_e32 v7, v139, v195
	v_fmac_f32_e32 v3, v139, v199
	v_fmac_f32_e32 v6, v140, v228
	v_fmac_f32_e32 v7, v140, v232
	v_fmac_f32_e32 v3, v140, v236
	v_fmac_f32_e32 v6, v141, v229
	v_fmac_f32_e32 v7, v141, v233
	v_fmac_f32_e32 v3, v141, v237
	v_fmac_f32_e32 v6, v142, v230
	v_fmac_f32_e32 v7, v142, v234
	v_fmac_f32_e32 v3, v142, v238
	v_fmac_f32_e32 v6, v143, v231
	v_fmac_f32_e32 v7, v143, v235
	v_fmac_f32_e32 v3, v143, v239
	global_load_dword v128, v[184:185], off nt
	v_add_co_u32_e32 v184, vcc, 0x6000, v184
	s_nop 1
	v_addc_co_u32_e32 v185, vcc, 0, v185, vcc
	global_load_dword v129, v[184:185], off nt
	v_add_co_u32_e32 v184, vcc, 0x6000, v184
	s_nop 1
	v_addc_co_u32_e32 v185, vcc, 0, v185, vcc
	global_load_dword v130, v[184:185], off nt
	v_add_co_u32_e32 v184, vcc, 0x6000, v184
	s_nop 1
	v_addc_co_u32_e32 v185, vcc, 0, v185, vcc
	global_load_dword v131, v[184:185], off nt
	v_add_co_u32_e32 v184, vcc, 0x6000, v184
	s_nop 1
	v_addc_co_u32_e32 v185, vcc, 0, v185, vcc
	global_load_dword v132, v[184:185], off nt
	v_add_co_u32_e32 v184, vcc, 0x6000, v184
	s_nop 1
	v_addc_co_u32_e32 v185, vcc, 0, v185, vcc
	global_load_dword v133, v[184:185], off nt
	v_add_co_u32_e32 v184, vcc, 0x6000, v184
	s_nop 1
	v_addc_co_u32_e32 v185, vcc, 0, v185, vcc
	global_load_dword v134, v[184:185], off nt
	v_add_co_u32_e32 v184, vcc, 0x6000, v184
	s_nop 1
	v_addc_co_u32_e32 v185, vcc, 0, v185, vcc
	global_load_dword v135, v[184:185], off nt
	v_add_co_u32_e32 v184, vcc, 0x6000, v184
	s_nop 1
	v_addc_co_u32_e32 v185, vcc, 0, v185, vcc
	global_load_dword v136, v[184:185], off nt
	v_add_co_u32_e32 v184, vcc, 0x6000, v184
	s_nop 1
	v_addc_co_u32_e32 v185, vcc, 0, v185, vcc
	global_load_dword v137, v[184:185], off nt
	v_add_co_u32_e32 v184, vcc, 0x6000, v184
	s_nop 1
	v_addc_co_u32_e32 v185, vcc, 0, v185, vcc
	global_load_dword v138, v[184:185], off nt
	v_add_co_u32_e32 v184, vcc, 0x6000, v184
	s_nop 1
	v_addc_co_u32_e32 v185, vcc, 0, v185, vcc
	global_load_dword v139, v[184:185], off nt
	v_add_co_u32_e32 v184, vcc, 0x6000, v184
	s_nop 1
	v_addc_co_u32_e32 v185, vcc, 0, v185, vcc
	global_load_dword v140, v[184:185], off nt
	v_add_co_u32_e32 v184, vcc, 0x6000, v184
	s_nop 1
	v_addc_co_u32_e32 v185, vcc, 0, v185, vcc
	global_load_dword v141, v[184:185], off nt
	v_add_co_u32_e32 v184, vcc, 0x6000, v184
	s_nop 1
	v_addc_co_u32_e32 v185, vcc, 0, v185, vcc
	global_load_dword v142, v[184:185], off nt
	v_add_co_u32_e32 v184, vcc, 0x6000, v184
	s_nop 1
	v_addc_co_u32_e32 v185, vcc, 0, v185, vcc
	global_load_dword v143, v[184:185], off nt
	v_add_co_u32_e32 v184, vcc, 0x6000, v184
	s_nop 1
	v_addc_co_u32_e32 v185, vcc, 0, v185, vcc
	ds_read_b128 v[8:11], v186 offset:128
	ds_read_b128 v[12:15], v186 offset:4224
	ds_read_b128 v[16:19], v186 offset:8320
	ds_read_b128 v[20:23], v186 offset:144
	ds_read_b128 v[24:27], v186 offset:4240
	ds_read_b128 v[28:31], v186 offset:8336
	ds_read_b128 v[188:191], v186 offset:160
	ds_read_b128 v[192:195], v186 offset:4256
	ds_read_b128 v[196:199], v186 offset:8352
	ds_read_b128 v[228:231], v186 offset:176
	ds_read_b128 v[232:235], v186 offset:4272
	ds_read_b128 v[236:239], v186 offset:8368
	s_waitcnt vmcnt(32)
	s_waitcnt lgkmcnt(0)
	v_fmac_f32_e32 v6, v144, v8
	v_fmac_f32_e32 v7, v144, v12
	v_fmac_f32_e32 v3, v144, v16
	v_fmac_f32_e32 v6, v145, v9
	v_fmac_f32_e32 v7, v145, v13
	v_fmac_f32_e32 v3, v145, v17
	v_fmac_f32_e32 v6, v146, v10
	v_fmac_f32_e32 v7, v146, v14
	v_fmac_f32_e32 v3, v146, v18
	v_fmac_f32_e32 v6, v147, v11
	v_fmac_f32_e32 v7, v147, v15
	v_fmac_f32_e32 v3, v147, v19
	v_fmac_f32_e32 v6, v148, v20
	v_fmac_f32_e32 v7, v148, v24
	v_fmac_f32_e32 v3, v148, v28
	v_fmac_f32_e32 v6, v149, v21
	v_fmac_f32_e32 v7, v149, v25
	v_fmac_f32_e32 v3, v149, v29
	v_fmac_f32_e32 v6, v150, v22
	v_fmac_f32_e32 v7, v150, v26
	v_fmac_f32_e32 v3, v150, v30
	v_fmac_f32_e32 v6, v151, v23
	v_fmac_f32_e32 v7, v151, v27
	v_fmac_f32_e32 v3, v151, v31
	v_fmac_f32_e32 v6, v152, v188
	v_fmac_f32_e32 v7, v152, v192
	v_fmac_f32_e32 v3, v152, v196
	v_fmac_f32_e32 v6, v153, v189
	v_fmac_f32_e32 v7, v153, v193
	v_fmac_f32_e32 v3, v153, v197
	v_fmac_f32_e32 v6, v154, v190
	v_fmac_f32_e32 v7, v154, v194
	v_fmac_f32_e32 v3, v154, v198
	v_fmac_f32_e32 v6, v155, v191
	v_fmac_f32_e32 v7, v155, v195
	v_fmac_f32_e32 v3, v155, v199
	v_fmac_f32_e32 v6, v156, v228
	v_fmac_f32_e32 v7, v156, v232
	v_fmac_f32_e32 v3, v156, v236
	v_fmac_f32_e32 v6, v157, v229
	v_fmac_f32_e32 v7, v157, v233
	v_fmac_f32_e32 v3, v157, v237
	v_fmac_f32_e32 v6, v158, v230
	v_fmac_f32_e32 v7, v158, v234
	v_fmac_f32_e32 v3, v158, v238
	v_fmac_f32_e32 v6, v159, v231
	v_fmac_f32_e32 v7, v159, v235
	v_fmac_f32_e32 v3, v159, v239
	global_load_dword v144, v[184:185], off nt
	v_add_co_u32_e32 v184, vcc, 0x6000, v184
	s_nop 1
	v_addc_co_u32_e32 v185, vcc, 0, v185, vcc
	global_load_dword v145, v[184:185], off nt
	v_add_co_u32_e32 v184, vcc, 0x6000, v184
	s_nop 1
	v_addc_co_u32_e32 v185, vcc, 0, v185, vcc
	global_load_dword v146, v[184:185], off nt
	v_add_co_u32_e32 v184, vcc, 0x6000, v184
	s_nop 1
	v_addc_co_u32_e32 v185, vcc, 0, v185, vcc
	global_load_dword v147, v[184:185], off nt
	v_add_co_u32_e32 v184, vcc, 0x6000, v184
	s_nop 1
	v_addc_co_u32_e32 v185, vcc, 0, v185, vcc
	global_load_dword v148, v[184:185], off nt
	v_add_co_u32_e32 v184, vcc, 0x6000, v184
	s_nop 1
	v_addc_co_u32_e32 v185, vcc, 0, v185, vcc
	global_load_dword v149, v[184:185], off nt
	v_add_co_u32_e32 v184, vcc, 0x6000, v184
	s_nop 1
	v_addc_co_u32_e32 v185, vcc, 0, v185, vcc
	global_load_dword v150, v[184:185], off nt
	v_add_co_u32_e32 v184, vcc, 0x6000, v184
	s_nop 1
	v_addc_co_u32_e32 v185, vcc, 0, v185, vcc
	global_load_dword v151, v[184:185], off nt
	v_add_co_u32_e32 v184, vcc, 0x6000, v184
	s_nop 1
	v_addc_co_u32_e32 v185, vcc, 0, v185, vcc
	global_load_dword v152, v[184:185], off nt
	v_add_co_u32_e32 v184, vcc, 0x6000, v184
	s_nop 1
	v_addc_co_u32_e32 v185, vcc, 0, v185, vcc
	global_load_dword v153, v[184:185], off nt
	v_add_co_u32_e32 v184, vcc, 0x6000, v184
	s_nop 1
	v_addc_co_u32_e32 v185, vcc, 0, v185, vcc
	global_load_dword v154, v[184:185], off nt
	v_add_co_u32_e32 v184, vcc, 0x6000, v184
	s_nop 1
	v_addc_co_u32_e32 v185, vcc, 0, v185, vcc
	global_load_dword v155, v[184:185], off nt
	v_add_co_u32_e32 v184, vcc, 0x6000, v184
	s_nop 1
	v_addc_co_u32_e32 v185, vcc, 0, v185, vcc
	global_load_dword v156, v[184:185], off nt
	v_add_co_u32_e32 v184, vcc, 0x6000, v184
	s_nop 1
	v_addc_co_u32_e32 v185, vcc, 0, v185, vcc
	global_load_dword v157, v[184:185], off nt
	v_add_co_u32_e32 v184, vcc, 0x6000, v184
	s_nop 1
	v_addc_co_u32_e32 v185, vcc, 0, v185, vcc
	global_load_dword v158, v[184:185], off nt
	v_add_co_u32_e32 v184, vcc, 0x6000, v184
	s_nop 1
	v_addc_co_u32_e32 v185, vcc, 0, v185, vcc
	global_load_dword v159, v[184:185], off nt
	v_add_co_u32_e32 v184, vcc, 0x6000, v184
	s_nop 1
	v_addc_co_u32_e32 v185, vcc, 0, v185, vcc
	ds_read_b128 v[8:11], v186 offset:192
	ds_read_b128 v[12:15], v186 offset:4288
	ds_read_b128 v[16:19], v186 offset:8384
	ds_read_b128 v[20:23], v186 offset:208
	ds_read_b128 v[24:27], v186 offset:4304
	ds_read_b128 v[28:31], v186 offset:8400
	ds_read_b128 v[188:191], v186 offset:224
	ds_read_b128 v[192:195], v186 offset:4320
	ds_read_b128 v[196:199], v186 offset:8416
	ds_read_b128 v[228:231], v186 offset:240
	ds_read_b128 v[232:235], v186 offset:4336
	ds_read_b128 v[236:239], v186 offset:8432
	s_waitcnt vmcnt(32)
	s_waitcnt lgkmcnt(0)
	v_fmac_f32_e32 v6, v112, v8
	v_fmac_f32_e32 v7, v112, v12
	v_fmac_f32_e32 v3, v112, v16
	v_fmac_f32_e32 v6, v113, v9
	v_fmac_f32_e32 v7, v113, v13
	v_fmac_f32_e32 v3, v113, v17
	v_fmac_f32_e32 v6, v114, v10
	v_fmac_f32_e32 v7, v114, v14
	v_fmac_f32_e32 v3, v114, v18
	v_fmac_f32_e32 v6, v115, v11
	v_fmac_f32_e32 v7, v115, v15
	v_fmac_f32_e32 v3, v115, v19
	v_fmac_f32_e32 v6, v116, v20
	v_fmac_f32_e32 v7, v116, v24
	v_fmac_f32_e32 v3, v116, v28
	v_fmac_f32_e32 v6, v117, v21
	v_fmac_f32_e32 v7, v117, v25
	v_fmac_f32_e32 v3, v117, v29
	v_fmac_f32_e32 v6, v118, v22
	v_fmac_f32_e32 v7, v118, v26
	v_fmac_f32_e32 v3, v118, v30
	v_fmac_f32_e32 v6, v119, v23
	v_fmac_f32_e32 v7, v119, v27
	v_fmac_f32_e32 v3, v119, v31
	v_fmac_f32_e32 v6, v120, v188
	v_fmac_f32_e32 v7, v120, v192
	v_fmac_f32_e32 v3, v120, v196
	v_fmac_f32_e32 v6, v121, v189
	v_fmac_f32_e32 v7, v121, v193
	v_fmac_f32_e32 v3, v121, v197
	v_fmac_f32_e32 v6, v122, v190
	v_fmac_f32_e32 v7, v122, v194
	v_fmac_f32_e32 v3, v122, v198
	v_fmac_f32_e32 v6, v123, v191
	v_fmac_f32_e32 v7, v123, v195
	v_fmac_f32_e32 v3, v123, v199
	v_fmac_f32_e32 v6, v124, v228
	v_fmac_f32_e32 v7, v124, v232
	v_fmac_f32_e32 v3, v124, v236
	v_fmac_f32_e32 v6, v125, v229
	v_fmac_f32_e32 v7, v125, v233
	v_fmac_f32_e32 v3, v125, v237
	v_fmac_f32_e32 v6, v126, v230
	v_fmac_f32_e32 v7, v126, v234
	v_fmac_f32_e32 v3, v126, v238
	v_fmac_f32_e32 v6, v127, v231
	v_fmac_f32_e32 v7, v127, v235
	v_fmac_f32_e32 v3, v127, v239
	global_load_dword v112, v[184:185], off nt
	v_add_co_u32_e32 v184, vcc, 0x6000, v184
	s_nop 1
	v_addc_co_u32_e32 v185, vcc, 0, v185, vcc
	global_load_dword v113, v[184:185], off nt
	v_add_co_u32_e32 v184, vcc, 0x6000, v184
	s_nop 1
	v_addc_co_u32_e32 v185, vcc, 0, v185, vcc
	global_load_dword v114, v[184:185], off nt
	v_add_co_u32_e32 v184, vcc, 0x6000, v184
	s_nop 1
	v_addc_co_u32_e32 v185, vcc, 0, v185, vcc
	global_load_dword v115, v[184:185], off nt
	v_add_co_u32_e32 v184, vcc, 0x6000, v184
	s_nop 1
	v_addc_co_u32_e32 v185, vcc, 0, v185, vcc
	global_load_dword v116, v[184:185], off nt
	v_add_co_u32_e32 v184, vcc, 0x6000, v184
	s_nop 1
	v_addc_co_u32_e32 v185, vcc, 0, v185, vcc
	global_load_dword v117, v[184:185], off nt
	v_add_co_u32_e32 v184, vcc, 0x6000, v184
	s_nop 1
	v_addc_co_u32_e32 v185, vcc, 0, v185, vcc
	global_load_dword v118, v[184:185], off nt
	v_add_co_u32_e32 v184, vcc, 0x6000, v184
	s_nop 1
	v_addc_co_u32_e32 v185, vcc, 0, v185, vcc
	global_load_dword v119, v[184:185], off nt
	v_add_co_u32_e32 v184, vcc, 0x6000, v184
	s_nop 1
	v_addc_co_u32_e32 v185, vcc, 0, v185, vcc
	global_load_dword v120, v[184:185], off nt
	v_add_co_u32_e32 v184, vcc, 0x6000, v184
	s_nop 1
	v_addc_co_u32_e32 v185, vcc, 0, v185, vcc
	global_load_dword v121, v[184:185], off nt
	v_add_co_u32_e32 v184, vcc, 0x6000, v184
	s_nop 1
	v_addc_co_u32_e32 v185, vcc, 0, v185, vcc
	global_load_dword v122, v[184:185], off nt
	v_add_co_u32_e32 v184, vcc, 0x6000, v184
	s_nop 1
	v_addc_co_u32_e32 v185, vcc, 0, v185, vcc
	global_load_dword v123, v[184:185], off nt
	v_add_co_u32_e32 v184, vcc, 0x6000, v184
	s_nop 1
	v_addc_co_u32_e32 v185, vcc, 0, v185, vcc
	global_load_dword v124, v[184:185], off nt
	v_add_co_u32_e32 v184, vcc, 0x6000, v184
	s_nop 1
	v_addc_co_u32_e32 v185, vcc, 0, v185, vcc
	global_load_dword v125, v[184:185], off nt
	v_add_co_u32_e32 v184, vcc, 0x6000, v184
	s_nop 1
	v_addc_co_u32_e32 v185, vcc, 0, v185, vcc
	global_load_dword v126, v[184:185], off nt
	v_add_co_u32_e32 v184, vcc, 0x6000, v184
	s_nop 1
	v_addc_co_u32_e32 v185, vcc, 0, v185, vcc
	global_load_dword v127, v[184:185], off nt
	v_add_co_u32_e32 v184, vcc, 0x6000, v184
	s_nop 1
	v_addc_co_u32_e32 v185, vcc, 0, v185, vcc
	ds_read_b128 v[8:11], v186 offset:256
	ds_read_b128 v[12:15], v186 offset:4352
	ds_read_b128 v[16:19], v186 offset:8448
	ds_read_b128 v[20:23], v186 offset:272
	ds_read_b128 v[24:27], v186 offset:4368
	ds_read_b128 v[28:31], v186 offset:8464
	ds_read_b128 v[188:191], v186 offset:288
	ds_read_b128 v[192:195], v186 offset:4384
	ds_read_b128 v[196:199], v186 offset:8480
	ds_read_b128 v[228:231], v186 offset:304
	ds_read_b128 v[232:235], v186 offset:4400
	ds_read_b128 v[236:239], v186 offset:8496
	s_waitcnt vmcnt(32)
	s_waitcnt lgkmcnt(0)
	v_fmac_f32_e32 v6, v128, v8
	v_fmac_f32_e32 v7, v128, v12
	v_fmac_f32_e32 v3, v128, v16
	v_fmac_f32_e32 v6, v129, v9
	v_fmac_f32_e32 v7, v129, v13
	v_fmac_f32_e32 v3, v129, v17
	v_fmac_f32_e32 v6, v130, v10
	v_fmac_f32_e32 v7, v130, v14
	v_fmac_f32_e32 v3, v130, v18
	v_fmac_f32_e32 v6, v131, v11
	v_fmac_f32_e32 v7, v131, v15
	v_fmac_f32_e32 v3, v131, v19
	v_fmac_f32_e32 v6, v132, v20
	v_fmac_f32_e32 v7, v132, v24
	v_fmac_f32_e32 v3, v132, v28
	v_fmac_f32_e32 v6, v133, v21
	v_fmac_f32_e32 v7, v133, v25
	v_fmac_f32_e32 v3, v133, v29
	v_fmac_f32_e32 v6, v134, v22
	v_fmac_f32_e32 v7, v134, v26
	v_fmac_f32_e32 v3, v134, v30
	v_fmac_f32_e32 v6, v135, v23
	v_fmac_f32_e32 v7, v135, v27
	v_fmac_f32_e32 v3, v135, v31
	v_fmac_f32_e32 v6, v136, v188
	v_fmac_f32_e32 v7, v136, v192
	v_fmac_f32_e32 v3, v136, v196
	v_fmac_f32_e32 v6, v137, v189
	v_fmac_f32_e32 v7, v137, v193
	v_fmac_f32_e32 v3, v137, v197
	v_fmac_f32_e32 v6, v138, v190
	v_fmac_f32_e32 v7, v138, v194
	v_fmac_f32_e32 v3, v138, v198
	v_fmac_f32_e32 v6, v139, v191
	v_fmac_f32_e32 v7, v139, v195
	v_fmac_f32_e32 v3, v139, v199
	v_fmac_f32_e32 v6, v140, v228
	v_fmac_f32_e32 v7, v140, v232
	v_fmac_f32_e32 v3, v140, v236
	v_fmac_f32_e32 v6, v141, v229
	v_fmac_f32_e32 v7, v141, v233
	v_fmac_f32_e32 v3, v141, v237
	v_fmac_f32_e32 v6, v142, v230
	v_fmac_f32_e32 v7, v142, v234
	v_fmac_f32_e32 v3, v142, v238
	v_fmac_f32_e32 v6, v143, v231
	v_fmac_f32_e32 v7, v143, v235
	v_fmac_f32_e32 v3, v143, v239
	global_load_dword v128, v[184:185], off nt
	v_add_co_u32_e32 v184, vcc, 0x6000, v184
	s_nop 1
	v_addc_co_u32_e32 v185, vcc, 0, v185, vcc
	global_load_dword v129, v[184:185], off nt
	v_add_co_u32_e32 v184, vcc, 0x6000, v184
	s_nop 1
	v_addc_co_u32_e32 v185, vcc, 0, v185, vcc
	global_load_dword v130, v[184:185], off nt
	v_add_co_u32_e32 v184, vcc, 0x6000, v184
	s_nop 1
	v_addc_co_u32_e32 v185, vcc, 0, v185, vcc
	global_load_dword v131, v[184:185], off nt
	v_add_co_u32_e32 v184, vcc, 0x6000, v184
	s_nop 1
	v_addc_co_u32_e32 v185, vcc, 0, v185, vcc
	global_load_dword v132, v[184:185], off nt
	v_add_co_u32_e32 v184, vcc, 0x6000, v184
	s_nop 1
	v_addc_co_u32_e32 v185, vcc, 0, v185, vcc
	global_load_dword v133, v[184:185], off nt
	v_add_co_u32_e32 v184, vcc, 0x6000, v184
	s_nop 1
	v_addc_co_u32_e32 v185, vcc, 0, v185, vcc
	global_load_dword v134, v[184:185], off nt
	v_add_co_u32_e32 v184, vcc, 0x6000, v184
	s_nop 1
	v_addc_co_u32_e32 v185, vcc, 0, v185, vcc
	global_load_dword v135, v[184:185], off nt
	v_add_co_u32_e32 v184, vcc, 0x6000, v184
	s_nop 1
	v_addc_co_u32_e32 v185, vcc, 0, v185, vcc
	global_load_dword v136, v[184:185], off nt
	v_add_co_u32_e32 v184, vcc, 0x6000, v184
	s_nop 1
	v_addc_co_u32_e32 v185, vcc, 0, v185, vcc
	global_load_dword v137, v[184:185], off nt
	v_add_co_u32_e32 v184, vcc, 0x6000, v184
	s_nop 1
	v_addc_co_u32_e32 v185, vcc, 0, v185, vcc
	global_load_dword v138, v[184:185], off nt
	v_add_co_u32_e32 v184, vcc, 0x6000, v184
	s_nop 1
	v_addc_co_u32_e32 v185, vcc, 0, v185, vcc
	global_load_dword v139, v[184:185], off nt
	v_add_co_u32_e32 v184, vcc, 0x6000, v184
	s_nop 1
	v_addc_co_u32_e32 v185, vcc, 0, v185, vcc
	global_load_dword v140, v[184:185], off nt
	v_add_co_u32_e32 v184, vcc, 0x6000, v184
	s_nop 1
	v_addc_co_u32_e32 v185, vcc, 0, v185, vcc
	global_load_dword v141, v[184:185], off nt
	v_add_co_u32_e32 v184, vcc, 0x6000, v184
	s_nop 1
	v_addc_co_u32_e32 v185, vcc, 0, v185, vcc
	global_load_dword v142, v[184:185], off nt
	v_add_co_u32_e32 v184, vcc, 0x6000, v184
	s_nop 1
	v_addc_co_u32_e32 v185, vcc, 0, v185, vcc
	global_load_dword v143, v[184:185], off nt
	v_add_co_u32_e32 v184, vcc, 0x6000, v184
	s_nop 1
	v_addc_co_u32_e32 v185, vcc, 0, v185, vcc
	ds_read_b128 v[8:11], v186 offset:320
	ds_read_b128 v[12:15], v186 offset:4416
	ds_read_b128 v[16:19], v186 offset:8512
	ds_read_b128 v[20:23], v186 offset:336
	ds_read_b128 v[24:27], v186 offset:4432
	ds_read_b128 v[28:31], v186 offset:8528
	ds_read_b128 v[188:191], v186 offset:352
	ds_read_b128 v[192:195], v186 offset:4448
	ds_read_b128 v[196:199], v186 offset:8544
	ds_read_b128 v[228:231], v186 offset:368
	ds_read_b128 v[232:235], v186 offset:4464
	ds_read_b128 v[236:239], v186 offset:8560
	s_waitcnt vmcnt(32)
	s_waitcnt lgkmcnt(0)
	v_fmac_f32_e32 v6, v144, v8
	v_fmac_f32_e32 v7, v144, v12
	v_fmac_f32_e32 v3, v144, v16
	v_fmac_f32_e32 v6, v145, v9
	v_fmac_f32_e32 v7, v145, v13
	v_fmac_f32_e32 v3, v145, v17
	v_fmac_f32_e32 v6, v146, v10
	v_fmac_f32_e32 v7, v146, v14
	v_fmac_f32_e32 v3, v146, v18
	v_fmac_f32_e32 v6, v147, v11
	v_fmac_f32_e32 v7, v147, v15
	v_fmac_f32_e32 v3, v147, v19
	v_fmac_f32_e32 v6, v148, v20
	v_fmac_f32_e32 v7, v148, v24
	v_fmac_f32_e32 v3, v148, v28
	v_fmac_f32_e32 v6, v149, v21
	v_fmac_f32_e32 v7, v149, v25
	v_fmac_f32_e32 v3, v149, v29
	v_fmac_f32_e32 v6, v150, v22
	v_fmac_f32_e32 v7, v150, v26
	v_fmac_f32_e32 v3, v150, v30
	v_fmac_f32_e32 v6, v151, v23
	v_fmac_f32_e32 v7, v151, v27
	v_fmac_f32_e32 v3, v151, v31
	v_fmac_f32_e32 v6, v152, v188
	v_fmac_f32_e32 v7, v152, v192
	v_fmac_f32_e32 v3, v152, v196
	v_fmac_f32_e32 v6, v153, v189
	v_fmac_f32_e32 v7, v153, v193
	v_fmac_f32_e32 v3, v153, v197
	v_fmac_f32_e32 v6, v154, v190
	v_fmac_f32_e32 v7, v154, v194
	v_fmac_f32_e32 v3, v154, v198
	v_fmac_f32_e32 v6, v155, v191
	v_fmac_f32_e32 v7, v155, v195
	v_fmac_f32_e32 v3, v155, v199
	v_fmac_f32_e32 v6, v156, v228
	v_fmac_f32_e32 v7, v156, v232
	v_fmac_f32_e32 v3, v156, v236
	v_fmac_f32_e32 v6, v157, v229
	v_fmac_f32_e32 v7, v157, v233
	v_fmac_f32_e32 v3, v157, v237
	v_fmac_f32_e32 v6, v158, v230
	v_fmac_f32_e32 v7, v158, v234
	v_fmac_f32_e32 v3, v158, v238
	v_fmac_f32_e32 v6, v159, v231
	v_fmac_f32_e32 v7, v159, v235
	v_fmac_f32_e32 v3, v159, v239
	ds_read_b128 v[8:11], v186 offset:384
	ds_read_b128 v[12:15], v186 offset:4480
	ds_read_b128 v[16:19], v186 offset:8576
	ds_read_b128 v[20:23], v186 offset:400
	ds_read_b128 v[24:27], v186 offset:4496
	ds_read_b128 v[28:31], v186 offset:8592
	ds_read_b128 v[188:191], v186 offset:416
	ds_read_b128 v[192:195], v186 offset:4512
	ds_read_b128 v[196:199], v186 offset:8608
	ds_read_b128 v[228:231], v186 offset:432
	ds_read_b128 v[232:235], v186 offset:4528
	ds_read_b128 v[236:239], v186 offset:8624
	s_waitcnt vmcnt(16)
	s_waitcnt lgkmcnt(0)
	v_fmac_f32_e32 v6, v112, v8
	v_fmac_f32_e32 v7, v112, v12
	v_fmac_f32_e32 v3, v112, v16
	v_fmac_f32_e32 v6, v113, v9
	v_fmac_f32_e32 v7, v113, v13
	v_fmac_f32_e32 v3, v113, v17
	v_fmac_f32_e32 v6, v114, v10
	v_fmac_f32_e32 v7, v114, v14
	v_fmac_f32_e32 v3, v114, v18
	v_fmac_f32_e32 v6, v115, v11
	v_fmac_f32_e32 v7, v115, v15
	v_fmac_f32_e32 v3, v115, v19
	v_fmac_f32_e32 v6, v116, v20
	v_fmac_f32_e32 v7, v116, v24
	v_fmac_f32_e32 v3, v116, v28
	v_fmac_f32_e32 v6, v117, v21
	v_fmac_f32_e32 v7, v117, v25
	v_fmac_f32_e32 v3, v117, v29
	v_fmac_f32_e32 v6, v118, v22
	v_fmac_f32_e32 v7, v118, v26
	v_fmac_f32_e32 v3, v118, v30
	v_fmac_f32_e32 v6, v119, v23
	v_fmac_f32_e32 v7, v119, v27
	v_fmac_f32_e32 v3, v119, v31
	v_fmac_f32_e32 v6, v120, v188
	v_fmac_f32_e32 v7, v120, v192
	v_fmac_f32_e32 v3, v120, v196
	v_fmac_f32_e32 v6, v121, v189
	v_fmac_f32_e32 v7, v121, v193
	v_fmac_f32_e32 v3, v121, v197
	v_fmac_f32_e32 v6, v122, v190
	v_fmac_f32_e32 v7, v122, v194
	v_fmac_f32_e32 v3, v122, v198
	v_fmac_f32_e32 v6, v123, v191
	v_fmac_f32_e32 v7, v123, v195
	v_fmac_f32_e32 v3, v123, v199
	v_fmac_f32_e32 v6, v124, v228
	v_fmac_f32_e32 v7, v124, v232
	v_fmac_f32_e32 v3, v124, v236
	v_fmac_f32_e32 v6, v125, v229
	v_fmac_f32_e32 v7, v125, v233
	v_fmac_f32_e32 v3, v125, v237
	v_fmac_f32_e32 v6, v126, v230
	v_fmac_f32_e32 v7, v126, v234
	v_fmac_f32_e32 v3, v126, v238
	v_fmac_f32_e32 v6, v127, v231
	v_fmac_f32_e32 v7, v127, v235
	v_fmac_f32_e32 v3, v127, v239
	ds_read_b128 v[8:11], v186 offset:448
	ds_read_b128 v[12:15], v186 offset:4544
	ds_read_b128 v[16:19], v186 offset:8640
	ds_read_b128 v[20:23], v186 offset:464
	ds_read_b128 v[24:27], v186 offset:4560
	ds_read_b128 v[28:31], v186 offset:8656
	ds_read_b128 v[188:191], v186 offset:480
	ds_read_b128 v[192:195], v186 offset:4576
	ds_read_b128 v[196:199], v186 offset:8672
	ds_read_b128 v[228:231], v186 offset:496
	ds_read_b128 v[232:235], v186 offset:4592
	ds_read_b128 v[236:239], v186 offset:8688
	s_waitcnt vmcnt(0)
	s_waitcnt lgkmcnt(0)
	v_fmac_f32_e32 v6, v128, v8
	v_fmac_f32_e32 v7, v128, v12
	v_fmac_f32_e32 v3, v128, v16
	v_fmac_f32_e32 v6, v129, v9
	v_fmac_f32_e32 v7, v129, v13
	v_fmac_f32_e32 v3, v129, v17
	v_fmac_f32_e32 v6, v130, v10
	v_fmac_f32_e32 v7, v130, v14
	v_fmac_f32_e32 v3, v130, v18
	v_fmac_f32_e32 v6, v131, v11
	v_fmac_f32_e32 v7, v131, v15
	v_fmac_f32_e32 v3, v131, v19
	v_fmac_f32_e32 v6, v132, v20
	v_fmac_f32_e32 v7, v132, v24
	v_fmac_f32_e32 v3, v132, v28
	v_fmac_f32_e32 v6, v133, v21
	v_fmac_f32_e32 v7, v133, v25
	v_fmac_f32_e32 v3, v133, v29
	v_fmac_f32_e32 v6, v134, v22
	v_fmac_f32_e32 v7, v134, v26
	v_fmac_f32_e32 v3, v134, v30
	v_fmac_f32_e32 v6, v135, v23
	v_fmac_f32_e32 v7, v135, v27
	v_fmac_f32_e32 v3, v135, v31
	v_fmac_f32_e32 v6, v136, v188
	v_fmac_f32_e32 v7, v136, v192
	v_fmac_f32_e32 v3, v136, v196
	v_fmac_f32_e32 v6, v137, v189
	v_fmac_f32_e32 v7, v137, v193
	v_fmac_f32_e32 v3, v137, v197
	v_fmac_f32_e32 v6, v138, v190
	v_fmac_f32_e32 v7, v138, v194
	v_fmac_f32_e32 v3, v138, v198
	v_fmac_f32_e32 v6, v139, v191
	v_fmac_f32_e32 v7, v139, v195
	v_fmac_f32_e32 v3, v139, v199
	v_fmac_f32_e32 v6, v140, v228
	v_fmac_f32_e32 v7, v140, v232
	v_fmac_f32_e32 v3, v140, v236
	v_fmac_f32_e32 v6, v141, v229
	v_fmac_f32_e32 v7, v141, v233
	v_fmac_f32_e32 v3, v141, v237
	v_fmac_f32_e32 v6, v142, v230
	v_fmac_f32_e32 v7, v142, v234
	v_fmac_f32_e32 v3, v142, v238
	v_fmac_f32_e32 v6, v143, v231
	v_fmac_f32_e32 v7, v143, v235
	v_fmac_f32_e32 v3, v143, v239
	ds_write2st64_b32 v35, v6, v7 offset1:1
	ds_write_b32 v35, v3 offset:512
	s_waitcnt lgkmcnt(0)
	s_barrier
	s_and_saveexec_b64 s[18:19], s[40:41]
	s_cbranch_execz .LBB0_1225
	v_mov_b64_e32 v[4:5], s[70:71]
	s_movk_i32 s3, 0x6000
	v_mad_u64_u32 v[4:5], s[12:13], v2, s3, v[4:5]
	v_lshlrev_b32_e32 v0, 2, v0
	v_lshl_add_u64 v[4:5], v[4:5], 0, v[0:1]
	v_lshlrev_b32_e32 v6, 2, v34
	v_mov_b32_e32 v7, v1
	v_lshl_add_u64 v[4:5], v[4:5], 0, v[6:7]
	global_load_dword v14, v[4:5], off
	v_mad_u64_u32 v[2:3], s[12:13], v2, 3, v[36:37]
	v_readlane_b32 s12, v254, 49
	ds_read2st64_b32 v[4:5], v55 offset0:3 offset1:6
	ds_read2st64_b32 v[8:9], v55 offset0:9 offset1:12
	ds_read2st64_b32 v[10:11], v55 offset0:15 offset1:18
	ds_read_b32 v15, v54
	ds_read_b32 v16, v55 offset:5376
	v_readlane_b32 s13, v254, 50
	s_nop 1
	v_mov_b64_e32 v[12:13], s[12:13]
	v_mad_u64_u32 v[12:13], s[12:13], v2, s3, v[12:13]
	v_mad_i32_i24 v13, v3, s3, v13
	v_lshl_add_u64 v[2:3], v[12:13], 0, v[0:1]
	v_lshl_add_u64 v[2:3], v[2:3], 0, v[6:7]
	s_waitcnt vmcnt(0) lgkmcnt(1)
	v_add_f32_e32 v0, v14, v15
	v_add_f32_e32 v0, v0, v4
	v_add_f32_e32 v0, v0, v5
	v_add_f32_e32 v0, v0, v8
	v_add_f32_e32 v0, v0, v9
	v_add_f32_e32 v0, v0, v10
	v_add_f32_e32 v0, v0, v11
	s_waitcnt lgkmcnt(0)
	v_add_f32_e32 v0, v0, v16
	global_store_dword v[2:3], v0, off
